# phase-0 transposes: wave-private LDS staging so global stores are full 128-byte row segments
# speedup vs baseline: 1.2572x; 1.0076x over previous
; __device__ __forceinline__ void transpose_tile(const float* src, int ldn, int k0, int n0, u16* dst, int ldk, int mode, float* sm) {
;     ...
;     const int n = (tid >> 3) + 32 * i, kg = tid & 7;
;     unsigned v[8];
; #pragma unroll
;     for (int j = 0; j < 8; ++j) v[j] = f2bf(sm[(kg * 8 + j) * 65 + n]);
;     const int gn = n0 + n;
;     int drow = gn;
;     if (mode == 1) drow = (gn >> 5) * 64 + (gn & 31);
;     else if (mode == 2) drow = (gn >> 5) * 64 + 32 + (gn & 31);
;     *reinterpret_cast<uint4*>(&dst[(long)drow * ldk + k0 + kg * 8]) =
;         make_uint4(v[0] | (v[1] << 16), v[2] | (v[3] << 16), v[4] | (v[5] << 16), v[6] | (v[7] << 16));
; __device__ __forceinline__ void prep_phase(const Params& P, float* sm) {
;     ...
;   for (int tt = VBID; tt < NTR; tt += VGRID) {
;     int t = tt;
.Lmy_p0_tr:
	s_lshl_b32 s6, s2, 3
	s_add_u32 s6, s6, s3
	s_add_u32 s6, s6, 512
	s_and_b32 s7, s6, 0x7ff
	v_lshrrev_b32_e32 v7, 5, v3
	v_and_b32_e32 v8, 31, v3
	v_lshl_add_u32 v7, v7, 6, v8
	s_mul_i32 s78, s3, 0x2400
	s_add_u32 s78, s78, 0x8000
	v_mul_u32_u24_e32 v10, 0x90, v3
	v_add_u32_e32 v10, s78, v10
	v_lshrrev_b32_e32 v11, 3, v3
	v_and_b32_e32 v12, 7, v3
	v_mul_u32_u24_e32 v13, 0x90, v11
	v_lshl_add_u32 v13, v12, 4, v13
	v_add_u32_e32 v13, s78, v13

; __device__ __forceinline__ void transpose_tile(const float* src, int ldn, int k0, int n0, u16* dst, int ldk, int mode, float* sm) {
;     ...
;   for (int i = 0; i < 16; ++i) {
;     const int r = rr + 4 * i;
;     sm[r * 65 + cc] = src[(long)(k0 + r) * ldn + n0 + cc];
;   }
; __device__ __forceinline__ void prep_phase(const Params& P, float* sm) {
;     ...
;     int t = tt;
;     const float* src; u16* dst; int ldn, ldk, mode = 0, kt, ntl;
;     if (t < 384) { src = P.w_in_ab; dst = P.wt_in; ldn = 1536; ldk = 1024; kt = t / 24; ntl = t % 24; }
;     else if (t < 640) { t -= 384; src = P.w_out_ab; dst = P.wt_outab; ldn = 1024; ldk = 1024; kt = t / 16; ntl = t % 16; }
;     else if (t < 1408) { t -= 640; src = P.w_qkv; dst = P.wt_qkv; ldn = 3072; ldk = 1024; kt = t / 48; ntl = t % 48; }
;     else if (t < 1664) { t -= 1408; src = P.w_out_na; dst = P.wt_outna; ldn = 1024; ldk = 1024; kt = t / 16; ntl = t % 16; }
;     else if (t < 1664 + 2816) {
;       t -= 1664;
;       const int which = t / 704, tq = t % 704;
;       const int l = which & 1, isup = which >> 1;
;       src = (isup ? P.w_up : P.w_gate) + (long)l * 1024 * 2816;
;       dst = P.wt_gu + (long)l * 5632 * 1024;
;       ldn = 2816; ldk = 1024; mode = isup ? 2 : 1; kt = tq / 44; ntl = tq % 44;
;     } else {
;       t -= 1664 + 2816;
;       const int l = t / 704, tq = t % 704;
;       src = P.w_down + (long)l * 2816 * 1024;
;       dst = P.wt_dn + (long)l * 1024 * 2816;
;       ldn = 1024; ldk = 2816; kt = tq / 16; ntl = tq % 16;
;     }
;     transpose_tile(src, ldn, kt * 64, ntl * 64, dst, ldk, mode, sm);
.Lmy_p0_dec:
	s_load_dwordx2 s[8:9], s[4:5], s20
	s_load_dwordx2 s[10:11], s[4:5], s21
	s_lshl_b32 s72, s15, 6
	s_mul_i32 s72, s72, s12
	s_lshl_b32 s73, s16, 8
	s_add_u32 s72, s72, s73
	s_add_u32 s72, s72, s26
	s_lshl_b32 s73, s16, 6
	s_lshl_b32 s74, s16, 7
	s_cmp_eq_u32 s14, 2
	s_cselect_b32 s75, 32, 0
	s_add_u32 s74, s74, s75
	s_cmp_eq_u32 s14, 0
	s_cselect_b32 s73, s73, s74
	s_cselect_b64 s[76:77], -1, 0
	s_mul_i32 s73, s73, s13
	s_lshl_b32 s74, s15, 7
	s_add_u32 s73, s73, s74
	s_add_u32 s73, s73, s27
	v_mul_u32_u24_e32 v9, s13, v11
	v_lshl_add_u32 v9, v12, 4, v9
	s_lshl_b32 s79, s13, 3
	s_mul_i32 s80, s13, 40
	s_cmp_eq_u32 s14, 0
	s_cselect_b32 s80, s79, s80
	s_waitcnt vmcnt(0)
	s_waitcnt lgkmcnt(0)
	s_add_u32 s8, s8, s72
	s_addc_u32 s9, s9, 0
	s_add_u32 s10, s10, s73
	s_addc_u32 s11, s11, 0
	global_load_dword v64, v2, s[8:9]
	s_add_u32 s8, s8, s12
	s_addc_u32 s9, s9, 0
	global_load_dword v65, v2, s[8:9]
	s_add_u32 s8, s8, s12
	s_addc_u32 s9, s9, 0
	global_load_dword v66, v2, s[8:9]
	s_add_u32 s8, s8, s12
	s_addc_u32 s9, s9, 0
	global_load_dword v67, v2, s[8:9]
	s_add_u32 s8, s8, s12
	s_addc_u32 s9, s9, 0
	global_load_dword v68, v2, s[8:9]
	s_add_u32 s8, s8, s12
	s_addc_u32 s9, s9, 0
	global_load_dword v69, v2, s[8:9]
	s_add_u32 s8, s8, s12
	s_addc_u32 s9, s9, 0
	global_load_dword v70, v2, s[8:9]
	s_add_u32 s8, s8, s12
	s_addc_u32 s9, s9, 0
	global_load_dword v71, v2, s[8:9]
	s_add_u32 s8, s8, s12
	s_addc_u32 s9, s9, 0
	global_load_dword v72, v2, s[8:9]
	s_add_u32 s8, s8, s12
	s_addc_u32 s9, s9, 0
	global_load_dword v73, v2, s[8:9]
	s_add_u32 s8, s8, s12
	s_addc_u32 s9, s9, 0
	global_load_dword v74, v2, s[8:9]
	s_add_u32 s8, s8, s12
	s_addc_u32 s9, s9, 0
	global_load_dword v75, v2, s[8:9]
	s_add_u32 s8, s8, s12
	s_addc_u32 s9, s9, 0
	global_load_dword v76, v2, s[8:9]
	s_add_u32 s8, s8, s12
	s_addc_u32 s9, s9, 0
	global_load_dword v77, v2, s[8:9]
	s_add_u32 s8, s8, s12
	s_addc_u32 s9, s9, 0
	global_load_dword v78, v2, s[8:9]
	s_add_u32 s8, s8, s12
	s_addc_u32 s9, s9, 0
	global_load_dword v79, v2, s[8:9]
	s_add_u32 s8, s8, s12
	s_addc_u32 s9, s9, 0
	global_load_dword v80, v2, s[8:9]
	s_add_u32 s8, s8, s12
	s_addc_u32 s9, s9, 0
	global_load_dword v81, v2, s[8:9]
	s_add_u32 s8, s8, s12
	s_addc_u32 s9, s9, 0
	global_load_dword v82, v2, s[8:9]
	s_add_u32 s8, s8, s12
	s_addc_u32 s9, s9, 0
	global_load_dword v83, v2, s[8:9]
	s_add_u32 s8, s8, s12
	s_addc_u32 s9, s9, 0
	global_load_dword v84, v2, s[8:9]
	s_add_u32 s8, s8, s12
	s_addc_u32 s9, s9, 0
	global_load_dword v85, v2, s[8:9]
	s_add_u32 s8, s8, s12
	s_addc_u32 s9, s9, 0
	global_load_dword v86, v2, s[8:9]
	s_add_u32 s8, s8, s12
	s_addc_u32 s9, s9, 0
	global_load_dword v87, v2, s[8:9]
	s_add_u32 s8, s8, s12
	s_addc_u32 s9, s9, 0
	global_load_dword v88, v2, s[8:9]
	s_add_u32 s8, s8, s12
	s_addc_u32 s9, s9, 0
	global_load_dword v89, v2, s[8:9]
	s_add_u32 s8, s8, s12
	s_addc_u32 s9, s9, 0
	global_load_dword v90, v2, s[8:9]
	s_add_u32 s8, s8, s12
	s_addc_u32 s9, s9, 0
	global_load_dword v91, v2, s[8:9]
	s_add_u32 s8, s8, s12
	s_addc_u32 s9, s9, 0
	global_load_dword v92, v2, s[8:9]
	s_add_u32 s8, s8, s12
	s_addc_u32 s9, s9, 0
	global_load_dword v93, v2, s[8:9]
	s_add_u32 s8, s8, s12
	s_addc_u32 s9, s9, 0
	global_load_dword v94, v2, s[8:9]
	s_add_u32 s8, s8, s12
	s_addc_u32 s9, s9, 0
	global_load_dword v95, v2, s[8:9]
	s_add_u32 s8, s8, s12
	s_addc_u32 s9, s9, 0
	global_load_dword v96, v2, s[8:9]
	s_add_u32 s8, s8, s12
	s_addc_u32 s9, s9, 0
	global_load_dword v97, v2, s[8:9]
	s_add_u32 s8, s8, s12
	s_addc_u32 s9, s9, 0
	global_load_dword v98, v2, s[8:9]
	s_add_u32 s8, s8, s12
	s_addc_u32 s9, s9, 0
	global_load_dword v99, v2, s[8:9]
	s_add_u32 s8, s8, s12
	s_addc_u32 s9, s9, 0
	global_load_dword v100, v2, s[8:9]
	s_add_u32 s8, s8, s12
	s_addc_u32 s9, s9, 0
	global_load_dword v101, v2, s[8:9]
	s_add_u32 s8, s8, s12
	s_addc_u32 s9, s9, 0
	global_load_dword v102, v2, s[8:9]
	s_add_u32 s8, s8, s12
	s_addc_u32 s9, s9, 0
	global_load_dword v103, v2, s[8:9]
	s_add_u32 s8, s8, s12
	s_addc_u32 s9, s9, 0
	global_load_dword v104, v2, s[8:9]
	s_add_u32 s8, s8, s12
	s_addc_u32 s9, s9, 0
	global_load_dword v105, v2, s[8:9]
	s_add_u32 s8, s8, s12
	s_addc_u32 s9, s9, 0
	global_load_dword v106, v2, s[8:9]
	s_add_u32 s8, s8, s12
	s_addc_u32 s9, s9, 0
	global_load_dword v107, v2, s[8:9]
	s_add_u32 s8, s8, s12
	s_addc_u32 s9, s9, 0
	global_load_dword v108, v2, s[8:9]
	s_add_u32 s8, s8, s12
	s_addc_u32 s9, s9, 0
	global_load_dword v109, v2, s[8:9]
	s_add_u32 s8, s8, s12
	s_addc_u32 s9, s9, 0
	global_load_dword v110, v2, s[8:9]
	s_add_u32 s8, s8, s12
	s_addc_u32 s9, s9, 0
	global_load_dword v111, v2, s[8:9]
	s_add_u32 s8, s8, s12
	s_addc_u32 s9, s9, 0
	global_load_dword v112, v2, s[8:9]
	s_add_u32 s8, s8, s12
	s_addc_u32 s9, s9, 0
	global_load_dword v113, v2, s[8:9]
	s_add_u32 s8, s8, s12
	s_addc_u32 s9, s9, 0
	global_load_dword v114, v2, s[8:9]
	s_add_u32 s8, s8, s12
	s_addc_u32 s9, s9, 0
	global_load_dword v115, v2, s[8:9]
	s_add_u32 s8, s8, s12
	s_addc_u32 s9, s9, 0
	global_load_dword v116, v2, s[8:9]
	s_add_u32 s8, s8, s12
	s_addc_u32 s9, s9, 0
	global_load_dword v117, v2, s[8:9]
	s_add_u32 s8, s8, s12
	s_addc_u32 s9, s9, 0
	global_load_dword v118, v2, s[8:9]
	s_add_u32 s8, s8, s12
	s_addc_u32 s9, s9, 0
	global_load_dword v119, v2, s[8:9]
	s_add_u32 s8, s8, s12
	s_addc_u32 s9, s9, 0
	global_load_dword v120, v2, s[8:9]
	s_add_u32 s8, s8, s12
	s_addc_u32 s9, s9, 0
	global_load_dword v121, v2, s[8:9]
	s_add_u32 s8, s8, s12
	s_addc_u32 s9, s9, 0
	global_load_dword v122, v2, s[8:9]
	s_add_u32 s8, s8, s12
	s_addc_u32 s9, s9, 0
	global_load_dword v123, v2, s[8:9]
	s_add_u32 s8, s8, s12
	s_addc_u32 s9, s9, 0
	global_load_dword v124, v2, s[8:9]
	s_add_u32 s8, s8, s12
	s_addc_u32 s9, s9, 0
	global_load_dword v125, v2, s[8:9]
	s_add_u32 s8, s8, s12
	s_addc_u32 s9, s9, 0
	s_waitcnt vmcnt(60)
; __device__ __forceinline__ void transpose_tile(const float* src, int ldn, int k0, int n0, u16* dst, int ldk, int mode, float* sm) {
;     ...
; #pragma unroll
;   for (int i = 0; i < 2; ++i) {
;     const int n = (tid >> 3) + 32 * i, kg = tid & 7;
;     unsigned v[8];
; #pragma unroll
;     for (int j = 0; j < 8; ++j) v[j] = f2bf(sm[(kg * 8 + j) * 65 + n]);
;     const int gn = n0 + n;
;     int drow = gn;
;     if (mode == 1) drow = (gn >> 5) * 64 + (gn & 31);
;     else if (mode == 2) drow = (gn >> 5) * 64 + 32 + (gn & 31);
;     *reinterpret_cast<uint4*>(&dst[(long)drow * ldk + k0 + kg * 8]) =
;         make_uint4(v[0] | (v[1] << 16), v[2] | (v[3] << 16), v[4] | (v[5] << 16), v[6] | (v[7] << 16));
;   }
	global_load_dword v126, v2, s[8:9]
	s_add_u32 s8, s8, s12
	s_addc_u32 s9, s9, 0
	global_load_dword v127, v2, s[8:9]
	s_waitcnt vmcnt(56)
	v_cvt_pk_bf16_f32 v64, v64, v65
	v_cvt_pk_bf16_f32 v65, v66, v67
	v_cvt_pk_bf16_f32 v66, v68, v69
	v_cvt_pk_bf16_f32 v67, v70, v71
	s_waitcnt vmcnt(48)
	v_cvt_pk_bf16_f32 v68, v72, v73
	v_cvt_pk_bf16_f32 v69, v74, v75
	v_cvt_pk_bf16_f32 v70, v76, v77
	v_cvt_pk_bf16_f32 v71, v78, v79
	s_waitcnt vmcnt(40)
	v_cvt_pk_bf16_f32 v72, v80, v81
	v_cvt_pk_bf16_f32 v73, v82, v83
	v_cvt_pk_bf16_f32 v74, v84, v85
	v_cvt_pk_bf16_f32 v75, v86, v87
	s_waitcnt vmcnt(32)
	v_cvt_pk_bf16_f32 v76, v88, v89
	v_cvt_pk_bf16_f32 v77, v90, v91
	v_cvt_pk_bf16_f32 v78, v92, v93
	v_cvt_pk_bf16_f32 v79, v94, v95
	s_waitcnt vmcnt(24)
	v_cvt_pk_bf16_f32 v80, v96, v97
	v_cvt_pk_bf16_f32 v81, v98, v99
	v_cvt_pk_bf16_f32 v82, v100, v101
	v_cvt_pk_bf16_f32 v83, v102, v103
	s_waitcnt vmcnt(16)
	v_cvt_pk_bf16_f32 v84, v104, v105
	v_cvt_pk_bf16_f32 v85, v106, v107
	v_cvt_pk_bf16_f32 v86, v108, v109
	v_cvt_pk_bf16_f32 v87, v110, v111
	s_waitcnt vmcnt(8)
	v_cvt_pk_bf16_f32 v88, v112, v113
	v_cvt_pk_bf16_f32 v89, v114, v115
	v_cvt_pk_bf16_f32 v90, v116, v117
	v_cvt_pk_bf16_f32 v91, v118, v119
	s_waitcnt vmcnt(0)
	v_cvt_pk_bf16_f32 v92, v120, v121
	v_cvt_pk_bf16_f32 v93, v122, v123
	v_cvt_pk_bf16_f32 v94, v124, v125
	v_cvt_pk_bf16_f32 v95, v126, v127
	ds_write_b128 v10, v[64:67] offset:0
	ds_write_b128 v10, v[68:71] offset:16
	ds_write_b128 v10, v[72:75] offset:32
	ds_write_b128 v10, v[76:79] offset:48
	ds_write_b128 v10, v[80:83] offset:64
	ds_write_b128 v10, v[84:87] offset:80
	ds_write_b128 v10, v[88:91] offset:96
	ds_write_b128 v10, v[92:95] offset:112
	s_waitcnt lgkmcnt(0)
	ds_read_b128 v[96:99], v13 offset:0
	ds_read_b128 v[100:103], v13 offset:1152
	ds_read_b128 v[104:107], v13 offset:2304
	ds_read_b128 v[108:111], v13 offset:3456
	ds_read_b128 v[112:115], v13 offset:4608
	ds_read_b128 v[116:119], v13 offset:5760
	ds_read_b128 v[120:123], v13 offset:6912
	ds_read_b128 v[124:127], v13 offset:8064
	s_waitcnt lgkmcnt(7)
	global_store_dwordx4 v9, v[96:99], s[10:11]
	s_add_u32 s10, s10, s79
	s_addc_u32 s11, s11, 0
	s_waitcnt lgkmcnt(6)
	global_store_dwordx4 v9, v[100:103], s[10:11]
	s_add_u32 s10, s10, s79
	s_addc_u32 s11, s11, 0
	s_waitcnt lgkmcnt(5)
	global_store_dwordx4 v9, v[104:107], s[10:11]
	s_add_u32 s10, s10, s79
	s_addc_u32 s11, s11, 0
	s_waitcnt lgkmcnt(4)
	global_store_dwordx4 v9, v[108:111], s[10:11]
	s_add_u32 s10, s10, s80
	s_addc_u32 s11, s11, 0
	s_waitcnt lgkmcnt(3)
	global_store_dwordx4 v9, v[112:115], s[10:11]
	s_add_u32 s10, s10, s79
	s_addc_u32 s11, s11, 0
	s_waitcnt lgkmcnt(2)
	global_store_dwordx4 v9, v[116:119], s[10:11]
	s_add_u32 s10, s10, s79
	s_addc_u32 s11, s11, 0
	s_waitcnt lgkmcnt(1)
	global_store_dwordx4 v9, v[120:123], s[10:11]
	s_add_u32 s10, s10, s79
	s_addc_u32 s11, s11, 0
	s_waitcnt lgkmcnt(0)
	global_store_dwordx4 v9, v[124:127], s[10:11]
	s_add_u32 s7, s7, 0x800
	s_cmp_lt_u32 s7, 5888
	s_cbranch_scc1 .Lmy_p0_tile
	s_mov_b64 s[0:1], 0
	s_mov_b64 s[34:35], s[96:97]
	v_readlane_b32 s96, v252, 52
	v_readlane_b32 s97, v252, 53
